# write-through (sc1) epilogue stores also in P1 (QKV) and P7 (kv_b/q_b), the other producers in front of grid barriers
# baseline (speedup 1.0000x reference)
.LBB0_236:
	s_ashr_i32 s52, s80, 2
	s_ashr_i32 s53, s52, 31
	s_lshl_b64 s[0:1], s[52:53], 25
	s_add_u32 s0, s70, s0
	s_addc_u32 s1, s71, s1
	s_cmp_lt_i32 s52, 2
	s_cselect_b32 s1, s1, s64
	s_cselect_b32 s0, s0, s63
	s_cmp_lt_u32 s80, 4
	s_cselect_b64 vcc, -1, 0
	s_lshl_b32 s39, s26, 8
	v_add_u32_e32 v164, s39, v1
	v_ashrrev_i32_e32 v165, 31, v164
	v_lshl_add_u64 v[148:149], v[164:165], 2, s[30:31]
	global_load_dword v152, v[148:149], off
	global_load_dword v153, v[148:149], off offset:64
	global_load_dword v154, v[148:149], off offset:128
	global_load_dword v155, v[148:149], off offset:192
	global_load_dword v156, v[148:149], off offset:512
	global_load_dword v157, v[148:149], off offset:576
	global_load_dword v158, v[148:149], off offset:640
	s_nop 0
	global_load_dword v148, v[148:149], off offset:704
	s_lshl_b32 s10, s80, 8
	s_and_b32 s10, s10, 0x300
	v_or_b32_e32 v138, s10, v169
	v_lshlrev_b32_e32 v138, 1, v138
	v_lshlrev_b64 v[150:151], 11, v[164:165]
	v_lshl_add_u64 v[166:167], s[0:1], 0, v[138:139]
	v_cndmask_b32_e32 v149, 1.0, v177, vcc
	v_lshl_add_u64 v[180:181], v[166:167], 0, v[150:151]
	s_cmp_lg_u32 s52, 1
	s_waitcnt vmcnt(0)
	v_fmamk_f32 v138, v152, 0x3a800000, v176
	v_fmamk_f32 v150, v153, 0x3a800000, v176
	v_cmp_gt_f32_e32 vcc, s83, v138
	v_fmamk_f32 v151, v154, 0x3a800000, v176
	v_fmamk_f32 v153, v156, 0x3a800000, v176
	v_mul_f32_e32 v156, 0x4b800000, v138
	v_cndmask_b32_e32 v138, v138, v156, vcc
	v_rsq_f32_e32 v138, v138
	v_fmamk_f32 v154, v157, 0x3a800000, v176
	v_mul_f32_e32 v157, 0x4b800000, v150
	v_mul_f32_e32 v161, 0x4b800000, v154
	v_cmp_gt_f32_e64 s[0:1], s83, v150
	v_cmp_gt_f32_e64 s[16:17], s83, v154
	v_fmamk_f32 v152, v155, 0x3a800000, v176
	v_fmamk_f32 v155, v158, 0x3a800000, v176
	v_cndmask_b32_e64 v150, v150, v157, s[0:1]
	v_cndmask_b32_e64 v154, v154, v161, s[16:17]
	v_mul_f32_e32 v162, 0x4b800000, v155
	v_cmp_gt_f32_e64 s[18:19], s83, v155
	v_rsq_f32_e32 v150, v150
	v_rsq_f32_e32 v157, v154
	v_mul_f32_e32 v154, 0x45800000, v138
	v_cndmask_b32_e64 v155, v155, v162, s[18:19]
	v_cndmask_b32_e32 v162, v138, v154, vcc
	v_mul_f32_e32 v138, v149, v162
	v_mul_f32_e32 v158, 0x4b800000, v151
	v_cmp_gt_f32_e64 s[10:11], s83, v151
	v_pk_mul_f32 v[186:187], v[128:129], v[138:139] op_sel_hi:[1,0]
	v_pk_mul_f32 v[184:185], v[126:127], v[138:139] op_sel_hi:[1,0]
	v_mul_f32_e32 v160, 0x4b800000, v153
	v_cndmask_b32_e64 v151, v151, v158, s[10:11]
	v_cmp_gt_f32_e64 s[14:15], s83, v153
	v_mul_f32_e32 v156, 0x45800000, v150
	v_pk_mul_f32 v[188:189], v[124:125], v[138:139] op_sel_hi:[1,0]
	v_pk_mul_f32 v[190:191], v[122:123], v[138:139] op_sel_hi:[1,0]
	v_cvt_pk_bf16_f32 v184, v184, v185
	v_cvt_pk_bf16_f32 v185, v186, v187
	v_cndmask_b32_e64 v153, v153, v160, s[14:15]
	v_cvt_pk_bf16_f32 v186, v190, v191
	v_cvt_pk_bf16_f32 v187, v188, v189
	v_rsq_f32_e32 v151, v151
	v_cndmask_b32_e64 v160, v150, v156, s[0:1]
	v_pk_mul_f32 v[192:193], v[64:65], v[138:139] op_sel_hi:[1,0]
	v_pk_mul_f32 v[194:195], v[62:63], v[138:139] op_sel_hi:[1,0]
	v_pk_mul_f32 v[196:197], v[60:61], v[138:139] op_sel_hi:[1,0]
	v_pk_mul_f32 v[198:199], v[58:59], v[138:139] op_sel_hi:[1,0]
	global_store_dwordx4 v[180:181], v[184:187], off sc1
	v_mul_f32_e32 v138, v149, v160
	v_mul_f32_e32 v159, 0x4b800000, v152
	v_cvt_pk_bf16_f32 v184, v194, v195
	v_cvt_pk_bf16_f32 v185, v192, v193
	v_cvt_pk_bf16_f32 v186, v198, v199
	v_cvt_pk_bf16_f32 v187, v196, v197
	global_store_dwordx4 v[180:181], v[184:187], off offset:256 sc1
	v_add_u32_e32 v180, s39, v170
	v_ashrrev_i32_e32 v181, 31, v180
	v_lshlrev_b64 v[180:181], 11, v[180:181]
	v_pk_mul_f32 v[186:187], v[120:121], v[138:139] op_sel_hi:[1,0]
	v_pk_mul_f32 v[184:185], v[118:119], v[138:139] op_sel_hi:[1,0]
	v_cmp_gt_f32_e64 s[12:13], s83, v152
	v_lshl_add_u64 v[180:181], v[166:167], 0, v[180:181]
	v_pk_mul_f32 v[188:189], v[116:117], v[138:139] op_sel_hi:[1,0]
	v_pk_mul_f32 v[190:191], v[114:115], v[138:139] op_sel_hi:[1,0]
	v_cvt_pk_bf16_f32 v184, v184, v185
	v_cvt_pk_bf16_f32 v185, v186, v187
	v_cndmask_b32_e64 v152, v152, v159, s[12:13]
	v_cvt_pk_bf16_f32 v186, v190, v191
	v_cvt_pk_bf16_f32 v187, v188, v189
	v_mul_f32_e32 v158, 0x45800000, v151
	global_store_dwordx4 v[180:181], v[184:187], off sc1
	v_rsq_f32_e32 v152, v152
	v_cndmask_b32_e64 v158, v151, v158, s[10:11]
	v_pk_mul_f32 v[186:187], v[56:57], v[138:139] op_sel_hi:[1,0]
	v_pk_mul_f32 v[184:185], v[54:55], v[138:139] op_sel_hi:[1,0]
	v_pk_mul_f32 v[188:189], v[52:53], v[138:139] op_sel_hi:[1,0]
	v_pk_mul_f32 v[190:191], v[50:51], v[138:139] op_sel_hi:[1,0]
	v_cvt_pk_bf16_f32 v184, v184, v185
	v_cvt_pk_bf16_f32 v185, v186, v187
	v_mul_f32_e32 v138, v149, v158
	v_cvt_pk_bf16_f32 v186, v190, v191
	v_cvt_pk_bf16_f32 v187, v188, v189
	global_store_dwordx4 v[180:181], v[184:187], off offset:256 sc1
	v_add_u32_e32 v180, s39, v171
	v_ashrrev_i32_e32 v181, 31, v180
	v_lshlrev_b64 v[180:181], 11, v[180:181]
	v_pk_mul_f32 v[186:187], v[112:113], v[138:139] op_sel_hi:[1,0]
	v_pk_mul_f32 v[184:185], v[110:111], v[138:139] op_sel_hi:[1,0]
	v_lshl_add_u64 v[180:181], v[166:167], 0, v[180:181]
	v_pk_mul_f32 v[188:189], v[108:109], v[138:139] op_sel_hi:[1,0]
	v_pk_mul_f32 v[190:191], v[106:107], v[138:139] op_sel_hi:[1,0]
	v_cvt_pk_bf16_f32 v184, v184, v185
	v_cvt_pk_bf16_f32 v185, v186, v187
	v_mul_f32_e32 v159, 0x45800000, v152
	v_cvt_pk_bf16_f32 v186, v190, v191
	v_cvt_pk_bf16_f32 v187, v188, v189
	global_store_dwordx4 v[180:181], v[184:187], off sc1
	v_rsq_f32_e32 v153, v153
	v_cndmask_b32_e64 v156, v152, v159, s[12:13]
	v_pk_mul_f32 v[186:187], v[48:49], v[138:139] op_sel_hi:[1,0]
	v_pk_mul_f32 v[184:185], v[46:47], v[138:139] op_sel_hi:[1,0]
	v_pk_mul_f32 v[188:189], v[44:45], v[138:139] op_sel_hi:[1,0]
	v_pk_mul_f32 v[190:191], v[42:43], v[138:139] op_sel_hi:[1,0]
	v_cvt_pk_bf16_f32 v184, v184, v185
	v_cvt_pk_bf16_f32 v185, v186, v187
	v_mul_f32_e32 v138, v149, v156
	v_cvt_pk_bf16_f32 v186, v190, v191
	v_cvt_pk_bf16_f32 v187, v188, v189
	global_store_dwordx4 v[180:181], v[184:187], off offset:256 sc1
	v_add_u32_e32 v180, s39, v172
	v_ashrrev_i32_e32 v181, 31, v180
	v_lshlrev_b64 v[180:181], 11, v[180:181]
	v_pk_mul_f32 v[186:187], v[104:105], v[138:139] op_sel_hi:[1,0]
	v_pk_mul_f32 v[184:185], v[102:103], v[138:139] op_sel_hi:[1,0]
	v_lshl_add_u64 v[180:181], v[166:167], 0, v[180:181]
	v_pk_mul_f32 v[188:189], v[100:101], v[138:139] op_sel_hi:[1,0]
	v_pk_mul_f32 v[190:191], v[98:99], v[138:139] op_sel_hi:[1,0]
	v_cvt_pk_bf16_f32 v184, v184, v185
	v_cvt_pk_bf16_f32 v185, v186, v187
	v_mul_f32_e32 v161, 0x45800000, v153
	v_cvt_pk_bf16_f32 v186, v190, v191
	v_cvt_pk_bf16_f32 v187, v188, v189
	global_store_dwordx4 v[180:181], v[184:187], off sc1
	v_cndmask_b32_e64 v154, v153, v161, s[14:15]
	v_pk_mul_f32 v[188:189], v[36:37], v[138:139] op_sel_hi:[1,0]
	v_pk_mul_f32 v[186:187], v[40:41], v[138:139] op_sel_hi:[1,0]
	v_pk_mul_f32 v[184:185], v[38:39], v[138:139] op_sel_hi:[1,0]
	v_pk_mul_f32 v[190:191], v[34:35], v[138:139] op_sel_hi:[1,0]
	v_cvt_pk_bf16_f32 v184, v184, v185
	v_cvt_pk_bf16_f32 v185, v186, v187
	v_mul_f32_e32 v138, v149, v154
	v_cvt_pk_bf16_f32 v186, v190, v191
	v_cvt_pk_bf16_f32 v187, v188, v189
	global_store_dwordx4 v[180:181], v[184:187], off offset:256 sc1
	v_add_u32_e32 v180, 0x80, v164
	v_ashrrev_i32_e32 v181, 31, v180
	v_fmamk_f32 v148, v148, 0x3a800000, v176
	v_lshlrev_b64 v[180:181], 11, v[180:181]
	v_pk_mul_f32 v[186:187], v[96:97], v[138:139] op_sel_hi:[1,0]
	v_pk_mul_f32 v[184:185], v[94:95], v[138:139] op_sel_hi:[1,0]
	v_mul_f32_e32 v163, 0x4b800000, v148
	v_cmp_gt_f32_e64 s[20:21], s83, v148
	v_lshl_add_u64 v[180:181], v[166:167], 0, v[180:181]
	v_pk_mul_f32 v[188:189], v[92:93], v[138:139] op_sel_hi:[1,0]
	v_pk_mul_f32 v[190:191], v[90:91], v[138:139] op_sel_hi:[1,0]
	v_cvt_pk_bf16_f32 v184, v184, v185
	v_cvt_pk_bf16_f32 v185, v186, v187
	v_cndmask_b32_e64 v148, v148, v163, s[20:21]
	v_cvt_pk_bf16_f32 v186, v190, v191
	v_cvt_pk_bf16_f32 v187, v188, v189
	v_mul_f32_e32 v163, 0x45800000, v157
	global_store_dwordx4 v[180:181], v[184:187], off sc1
	v_rsq_f32_e32 v155, v155
	v_cndmask_b32_e64 v152, v157, v163, s[16:17]
	v_pk_mul_f32 v[186:187], v[32:33], v[138:139] op_sel_hi:[1,0]
	v_pk_mul_f32 v[184:185], v[30:31], v[138:139] op_sel_hi:[1,0]
	v_pk_mul_f32 v[188:189], v[28:29], v[138:139] op_sel_hi:[1,0]
	v_pk_mul_f32 v[190:191], v[26:27], v[138:139] op_sel_hi:[1,0]
	v_cvt_pk_bf16_f32 v184, v184, v185
	v_cvt_pk_bf16_f32 v185, v186, v187
	v_mul_f32_e32 v138, v149, v152
	v_cvt_pk_bf16_f32 v186, v190, v191
	v_cvt_pk_bf16_f32 v187, v188, v189
	global_store_dwordx4 v[180:181], v[184:187], off offset:256 sc1
	v_add_u32_e32 v180, 0x90, v164
	v_ashrrev_i32_e32 v181, 31, v180
	v_lshlrev_b64 v[180:181], 11, v[180:181]
	v_pk_mul_f32 v[186:187], v[88:89], v[138:139] op_sel_hi:[1,0]
	v_pk_mul_f32 v[184:185], v[86:87], v[138:139] op_sel_hi:[1,0]
	v_rsq_f32_e32 v148, v148
	v_lshl_add_u64 v[180:181], v[166:167], 0, v[180:181]
	v_pk_mul_f32 v[188:189], v[84:85], v[138:139] op_sel_hi:[1,0]
	v_pk_mul_f32 v[190:191], v[82:83], v[138:139] op_sel_hi:[1,0]
	v_cvt_pk_bf16_f32 v184, v184, v185
	v_cvt_pk_bf16_f32 v185, v186, v187
	v_mul_f32_e32 v165, 0x45800000, v155
	v_cvt_pk_bf16_f32 v186, v190, v191
	v_cvt_pk_bf16_f32 v187, v188, v189
	global_store_dwordx4 v[180:181], v[184:187], off sc1
	v_cndmask_b32_e64 v150, v155, v165, s[18:19]
	v_pk_mul_f32 v[188:189], v[20:21], v[138:139] op_sel_hi:[1,0]
	v_pk_mul_f32 v[186:187], v[24:25], v[138:139] op_sel_hi:[1,0]
	v_pk_mul_f32 v[184:185], v[22:23], v[138:139] op_sel_hi:[1,0]
	v_pk_mul_f32 v[190:191], v[18:19], v[138:139] op_sel_hi:[1,0]
	v_cvt_pk_bf16_f32 v184, v184, v185
	v_cvt_pk_bf16_f32 v185, v186, v187
	v_mul_f32_e32 v138, v149, v150
	v_cvt_pk_bf16_f32 v186, v190, v191
	v_cvt_pk_bf16_f32 v187, v188, v189
	global_store_dwordx4 v[180:181], v[184:187], off offset:256 sc1
	v_add_u32_e32 v180, 0xa0, v164
	v_ashrrev_i32_e32 v181, 31, v180
	v_mul_f32_e32 v179, 0x45800000, v148
	v_lshlrev_b64 v[180:181], 11, v[180:181]
	v_pk_mul_f32 v[186:187], v[80:81], v[138:139] op_sel_hi:[1,0]
	v_pk_mul_f32 v[184:185], v[78:79], v[138:139] op_sel_hi:[1,0]
	v_add_u32_e32 v164, 0xb0, v164
	v_cndmask_b32_e64 v148, v148, v179, s[20:21]
	v_lshl_add_u64 v[180:181], v[166:167], 0, v[180:181]
	v_pk_mul_f32 v[188:189], v[76:77], v[138:139] op_sel_hi:[1,0]
	v_pk_mul_f32 v[190:191], v[74:75], v[138:139] op_sel_hi:[1,0]
	v_cvt_pk_bf16_f32 v184, v184, v185
	v_cvt_pk_bf16_f32 v185, v186, v187
	v_ashrrev_i32_e32 v165, 31, v164
	v_cvt_pk_bf16_f32 v186, v190, v191
	v_cvt_pk_bf16_f32 v187, v188, v189
	global_store_dwordx4 v[180:181], v[184:187], off sc1
	v_pk_mul_f32 v[188:189], v[12:13], v[138:139] op_sel_hi:[1,0]
	v_pk_mul_f32 v[190:191], v[10:11], v[138:139] op_sel_hi:[1,0]
	v_pk_mul_f32 v[186:187], v[16:17], v[138:139] op_sel_hi:[1,0]
	v_pk_mul_f32 v[184:185], v[14:15], v[138:139] op_sel_hi:[1,0]
	v_mul_f32_e32 v138, v149, v148
	v_lshlrev_b64 v[164:165], 11, v[164:165]
	v_cvt_pk_bf16_f32 v184, v184, v185
	v_cvt_pk_bf16_f32 v185, v186, v187
	v_cvt_pk_bf16_f32 v186, v190, v191
	v_cvt_pk_bf16_f32 v187, v188, v189
	global_store_dwordx4 v[180:181], v[184:187], off offset:256 sc1
	v_lshl_add_u64 v[180:181], v[166:167], 0, v[164:165]
	v_pk_mul_f32 v[166:167], v[72:73], v[138:139] op_sel_hi:[1,0]
	v_pk_mul_f32 v[164:165], v[70:71], v[138:139] op_sel_hi:[1,0]
	v_pk_mul_f32 v[184:185], v[68:69], v[138:139] op_sel_hi:[1,0]
	v_pk_mul_f32 v[186:187], v[66:67], v[138:139] op_sel_hi:[1,0]
	v_cvt_pk_bf16_f32 v164, v164, v165
	v_cvt_pk_bf16_f32 v165, v166, v167
	s_nop 0
	v_cvt_pk_bf16_f32 v166, v186, v187
	v_cvt_pk_bf16_f32 v167, v184, v185
	global_store_dwordx4 v[180:181], v[164:167], off sc1
	v_pk_mul_f32 v[184:185], v[4:5], v[138:139] op_sel_hi:[1,0]
	v_pk_mul_f32 v[186:187], v[2:3], v[138:139] op_sel_hi:[1,0]
	v_pk_mul_f32 v[166:167], v[8:9], v[138:139] op_sel_hi:[1,0]
	v_pk_mul_f32 v[164:165], v[6:7], v[138:139] op_sel_hi:[1,0]
	s_nop 0
	v_cvt_pk_bf16_f32 v164, v164, v165
	v_cvt_pk_bf16_f32 v165, v166, v167
	v_cvt_pk_bf16_f32 v166, v186, v187
	v_cvt_pk_bf16_f32 v167, v184, v185
	global_store_dwordx4 v[180:181], v[164:167], off offset:256 sc1
	s_cbranch_scc1 .LBB0_248
	v_pk_mul_f32 v[126:127], v[126:127], v[162:163] op_sel_hi:[1,0]
	v_pk_mul_f32 v[118:119], v[118:119], v[160:161] op_sel_hi:[1,0]
	v_and_b32_e32 v149, 64, v178
	v_pk_mul_f32 v[128:129], v[128:129], v[162:163] op_sel_hi:[1,0]
	v_mul_f32_e32 v127, v127, v127
	v_pk_mul_f32 v[120:121], v[120:121], v[160:161] op_sel_hi:[1,0]
	v_mul_f32_e32 v119, v119, v119
	v_pk_mul_f32 v[110:111], v[110:111], v[158:159] op_sel_hi:[1,0]
	v_pk_mul_f32 v[102:103], v[102:103], v[156:157] op_sel_hi:[1,0]
	v_add_u32_e32 v149, 64, v149
	v_xor_b32_e32 v151, 1, v178
	v_pk_mul_f32 v[122:123], v[122:123], v[162:163] op_sel_hi:[1,0]
	v_fmac_f32_e32 v127, v126, v126
	v_mul_f32_e32 v126, v129, v129
	v_pk_mul_f32 v[114:115], v[114:115], v[160:161] op_sel_hi:[1,0]
	v_fmac_f32_e32 v119, v118, v118
	v_mul_f32_e32 v118, v121, v121
	v_pk_mul_f32 v[112:113], v[112:113], v[158:159] op_sel_hi:[1,0]
	v_mul_f32_e32 v111, v111, v111
	v_pk_mul_f32 v[104:105], v[104:105], v[156:157] op_sel_hi:[1,0]
	v_mul_f32_e32 v103, v103, v103
	v_pk_mul_f32 v[94:95], v[94:95], v[154:155] op_sel_hi:[1,0]
	v_pk_mul_f32 v[86:87], v[86:87], v[152:153] op_sel_hi:[1,0]
	v_fmac_f32_e32 v126, v128, v128
	v_mul_f32_e32 v123, v123, v123
	v_fmac_f32_e32 v118, v120, v120
	v_mul_f32_e32 v115, v115, v115
	v_pk_mul_f32 v[106:107], v[106:107], v[158:159] op_sel_hi:[1,0]
	v_fmac_f32_e32 v111, v110, v110
	v_mul_f32_e32 v110, v113, v113
	v_pk_mul_f32 v[98:99], v[98:99], v[156:157] op_sel_hi:[1,0]
	v_fmac_f32_e32 v103, v102, v102
	v_mul_f32_e32 v102, v105, v105
	v_pk_mul_f32 v[96:97], v[96:97], v[154:155] op_sel_hi:[1,0]
	v_mul_f32_e32 v95, v95, v95
	v_pk_mul_f32 v[88:89], v[88:89], v[152:153] op_sel_hi:[1,0]
	v_mul_f32_e32 v87, v87, v87
	v_pk_mul_f32 v[78:79], v[78:79], v[150:151] op_sel_hi:[1,0]
	v_pk_mul_f32 v[70:71], v[70:71], v[148:149] op_sel_hi:[1,0]
	v_xor_b32_e32 v138, 16, v178
	v_pk_mul_f32 v[124:125], v[124:125], v[162:163] op_sel_hi:[1,0]
	v_add_f32_e32 v126, v127, v126
	v_fmac_f32_e32 v123, v122, v122
	v_pk_mul_f32 v[116:117], v[116:117], v[160:161] op_sel_hi:[1,0]
	v_add_f32_e32 v118, v119, v118
	v_fmac_f32_e32 v115, v114, v114
	v_fmac_f32_e32 v110, v112, v112
	v_mul_f32_e32 v107, v107, v107
	v_fmac_f32_e32 v102, v104, v104
	v_mul_f32_e32 v99, v99, v99
	v_pk_mul_f32 v[90:91], v[90:91], v[154:155] op_sel_hi:[1,0]
	v_fmac_f32_e32 v95, v94, v94
	v_mul_f32_e32 v94, v97, v97
	v_pk_mul_f32 v[82:83], v[82:83], v[152:153] op_sel_hi:[1,0]
	v_fmac_f32_e32 v87, v86, v86
	v_mul_f32_e32 v86, v89, v89
	v_pk_mul_f32 v[80:81], v[80:81], v[150:151] op_sel_hi:[1,0]
	v_mul_f32_e32 v79, v79, v79
	v_pk_mul_f32 v[72:73], v[72:73], v[148:149] op_sel_hi:[1,0]
	v_mul_f32_e32 v71, v71, v71
	v_cmp_lt_i32_e32 vcc, v138, v149
	v_add_f32_e32 v122, v123, v126
	v_mul_f32_e32 v123, v125, v125
	v_add_f32_e32 v114, v115, v118
	v_mul_f32_e32 v115, v117, v117
	v_pk_mul_f32 v[108:109], v[108:109], v[158:159] op_sel_hi:[1,0]
	v_add_f32_e32 v110, v111, v110
	v_fmac_f32_e32 v107, v106, v106
	v_pk_mul_f32 v[100:101], v[100:101], v[156:157] op_sel_hi:[1,0]
	v_add_f32_e32 v102, v103, v102
	v_fmac_f32_e32 v99, v98, v98
	v_fmac_f32_e32 v94, v96, v96
	v_mul_f32_e32 v91, v91, v91
	v_fmac_f32_e32 v86, v88, v88
	v_mul_f32_e32 v83, v83, v83
	v_pk_mul_f32 v[74:75], v[74:75], v[150:151] op_sel_hi:[1,0]
	v_fmac_f32_e32 v79, v78, v78
	v_mul_f32_e32 v78, v81, v81
	v_pk_mul_f32 v[66:67], v[66:67], v[148:149] op_sel_hi:[1,0]
	v_fmac_f32_e32 v71, v70, v70
	v_mul_f32_e32 v70, v73, v73
	v_cndmask_b32_e32 v138, v178, v138, vcc
	v_fmac_f32_e32 v123, v124, v124
	v_fmac_f32_e32 v115, v116, v116
	v_add_f32_e32 v106, v107, v110
	v_mul_f32_e32 v107, v109, v109
	v_add_f32_e32 v98, v99, v102
	v_mul_f32_e32 v99, v101, v101
	v_pk_mul_f32 v[92:93], v[92:93], v[154:155] op_sel_hi:[1,0]
	v_add_f32_e32 v94, v95, v94
	v_fmac_f32_e32 v91, v90, v90
	v_pk_mul_f32 v[84:85], v[84:85], v[152:153] op_sel_hi:[1,0]
	v_add_f32_e32 v86, v87, v86
	v_fmac_f32_e32 v83, v82, v82
	v_fmac_f32_e32 v78, v80, v80
	v_mul_f32_e32 v75, v75, v75
	v_fmac_f32_e32 v70, v72, v72
	v_mul_f32_e32 v67, v67, v67
	v_lshlrev_b32_e32 v164, 2, v138
	v_add_f32_e32 v122, v123, v122
	v_add_f32_e32 v115, v115, v114
	v_fmac_f32_e32 v107, v108, v108
	v_fmac_f32_e32 v99, v100, v100
	v_add_f32_e32 v90, v91, v94
	v_mul_f32_e32 v91, v93, v93
	v_add_f32_e32 v82, v83, v86
	v_mul_f32_e32 v83, v85, v85
	v_pk_mul_f32 v[76:77], v[76:77], v[150:151] op_sel_hi:[1,0]
	v_add_f32_e32 v78, v79, v78
	v_fmac_f32_e32 v75, v74, v74
	v_pk_mul_f32 v[68:69], v[68:69], v[148:149] op_sel_hi:[1,0]
	v_add_f32_e32 v70, v71, v70
	v_fmac_f32_e32 v67, v66, v66
	ds_bpermute_b32 v123, v164, v122
	ds_bpermute_b32 v116, v164, v115
	v_add_f32_e32 v106, v107, v106
	v_add_f32_e32 v98, v99, v98
	v_fmac_f32_e32 v91, v92, v92
	v_fmac_f32_e32 v83, v84, v84
	v_add_f32_e32 v74, v75, v78
	v_mul_f32_e32 v75, v77, v77
	v_add_f32_e32 v66, v67, v70
	v_mul_f32_e32 v67, v69, v69
	ds_bpermute_b32 v107, v164, v106
	ds_bpermute_b32 v99, v164, v98
	v_add_f32_e32 v90, v91, v90
	v_add_f32_e32 v82, v83, v82
	v_fmac_f32_e32 v75, v76, v76
	v_fmac_f32_e32 v67, v68, v68
	v_xor_b32_e32 v138, 32, v178
	ds_bpermute_b32 v91, v164, v90
	ds_bpermute_b32 v83, v164, v82
	v_add_f32_e32 v74, v75, v74
	v_add_f32_e32 v66, v67, v66
	v_cmp_lt_i32_e32 vcc, v138, v149
	ds_bpermute_b32 v75, v164, v74
	ds_bpermute_b32 v67, v164, v66
	v_cndmask_b32_e32 v138, v178, v138, vcc
	v_lshlrev_b32_e32 v138, 2, v138
	s_waitcnt lgkmcnt(7)
	v_add_f32_e32 v117, v122, v123
	s_waitcnt lgkmcnt(6)
	v_add_f32_e32 v115, v115, v116
	ds_bpermute_b32 v118, v138, v117
	ds_bpermute_b32 v116, v138, v115
	s_waitcnt lgkmcnt(7)
	v_add_f32_e32 v102, v106, v107
	s_waitcnt lgkmcnt(6)
	v_add_f32_e32 v98, v98, v99
	ds_bpermute_b32 v103, v138, v102
	ds_bpermute_b32 v99, v138, v98
	s_waitcnt lgkmcnt(7)
	v_add_f32_e32 v90, v90, v91
	s_waitcnt lgkmcnt(6)
	v_add_f32_e32 v68, v82, v83
	ds_bpermute_b32 v91, v138, v90
	ds_bpermute_b32 v69, v138, v68
	s_waitcnt lgkmcnt(7)
	v_add_f32_e32 v70, v74, v75
	s_waitcnt lgkmcnt(6)
	v_add_f32_e32 v66, v66, v67
	ds_bpermute_b32 v71, v138, v70
	ds_bpermute_b32 v67, v138, v66
	s_waitcnt lgkmcnt(7)
	v_add_f32_e32 v100, v117, v118
	s_waitcnt lgkmcnt(6)
	v_add_f32_e32 v101, v115, v116
	v_max3_f32 v92, v100, 0, v101
	s_waitcnt lgkmcnt(5)
	v_add_f32_e32 v93, v102, v103
	s_waitcnt lgkmcnt(4)
	v_add_f32_e32 v94, v98, v99
	v_cmp_lt_i32_e32 vcc, v151, v149
	v_max3_f32 v92, v92, v93, v94
	s_waitcnt lgkmcnt(3)
	v_add_f32_e32 v72, v90, v91
	s_waitcnt lgkmcnt(2)
	v_add_f32_e32 v68, v68, v69
	v_cndmask_b32_e32 v114, v178, v151, vcc
	v_max3_f32 v68, v92, v72, v68
	s_waitcnt lgkmcnt(1)
	v_add_f32_e32 v69, v70, v71
	s_waitcnt lgkmcnt(0)
	v_add_f32_e32 v66, v66, v67
	v_lshlrev_b32_e32 v114, 2, v114
	v_max3_f32 v67, v68, v69, v66
	ds_bpermute_b32 v68, v114, v67
	v_xor_b32_e32 v66, 2, v178
	v_cmp_lt_i32_e32 vcc, v66, v149
	s_waitcnt lgkmcnt(0)
	v_max_f32_e32 v68, v68, v68
	v_cndmask_b32_e32 v66, v178, v66, vcc
	v_lshlrev_b32_e32 v66, 2, v66
	v_max_f32_e32 v68, v67, v68
	ds_bpermute_b32 v69, v66, v68
	v_xor_b32_e32 v67, 4, v178
	v_cmp_lt_i32_e32 vcc, v67, v149
	s_waitcnt lgkmcnt(0)
	v_max_f32_e32 v69, v69, v69
	v_cndmask_b32_e32 v67, v178, v67, vcc
	v_lshlrev_b32_e32 v67, 2, v67
	v_max_f32_e32 v69, v68, v69
	ds_bpermute_b32 v70, v67, v69
	v_xor_b32_e32 v68, 8, v178
	v_cmp_lt_i32_e32 vcc, v68, v149
	s_waitcnt lgkmcnt(0)
	v_max_f32_e32 v70, v70, v70
	v_cndmask_b32_e32 v68, v178, v68, vcc
	v_lshlrev_b32_e32 v68, 2, v68
	v_max_f32_e32 v69, v69, v70
	ds_bpermute_b32 v70, v68, v69
	s_and_saveexec_b64 s[0:1], s[6:7]
	s_cbranch_execz .LBB0_242
	s_waitcnt lgkmcnt(0)
	v_max_f32_e32 v70, v70, v70
	v_max_f32_e32 v69, v69, v69
	s_mov_b64 s[10:11], exec
	v_max_f32_e32 v69, v69, v70
	s_mov_b32 s12, 0

.LBB0_1321:
	s_lshl_b32 s27, s6, 8
	s_add_i32 s27, s27, s62
	v_or_b32_e32 v142, s27, v1
	v_ashrrev_i32_e32 v143, 31, v142
	v_lshl_add_u64 v[140:141], v[142:143], 2, s[18:19]
	global_load_dword v151, v[140:141], off
	global_load_dword v158, v[140:141], off offset:64
	global_load_dword v159, v[140:141], off offset:128
	global_load_dword v160, v[140:141], off offset:192
	v_add_u32_e32 v246, s27, v145
	v_ashrrev_i32_e32 v247, 31, v246
	v_lshl_add_u64 v[246:247], v[246:247], 2, s[18:19]
	global_load_dword v238, v[246:247], off
	global_load_dword v239, v[246:247], off offset:64
	global_load_dword v240, v[246:247], off offset:128
	global_load_dword v241, v[246:247], off offset:192
	v_lshlrev_b64 v[156:157], 12, v[142:143]
	v_lshl_or_b32 v140, s0, 8, v146
	v_ashrrev_i32_e32 v141, 31, v140
	v_or_b32_e32 v152, 16, v142
	v_lshlrev_b64 v[140:141], 1, v[140:141]
	v_ashrrev_i32_e32 v153, 31, v152
	v_lshl_add_u64 v[156:157], s[16:17], 0, v[156:157]
	v_or_b32_e32 v154, 32, v142
	v_lshlrev_b64 v[152:153], 12, v[152:153]
	v_lshl_add_u64 v[156:157], v[156:157], 0, v[140:141]
	v_ashrrev_i32_e32 v155, 31, v154
	v_lshl_add_u64 v[152:153], s[16:17], 0, v[152:153]
	v_lshlrev_b64 v[154:155], 12, v[154:155]
	v_lshl_add_u64 v[152:153], v[152:153], 0, v[140:141]
	v_lshl_add_u64 v[154:155], s[16:17], 0, v[154:155]
	v_lshl_add_u64 v[154:155], v[154:155], 0, v[140:141]
	s_waitcnt vmcnt(4)
	v_fmamk_f32 v143, v151, 0x3b800000, v150
	v_fmamk_f32 v151, v158, 0x3b800000, v150
	v_fmamk_f32 v158, v159, 0x3b800000, v150
	v_fmamk_f32 v159, v160, 0x3b800000, v150
	v_mul_f32_e32 v160, 0x4b800000, v143
	v_mul_f32_e32 v161, 0x4b800000, v151
	v_mul_f32_e32 v162, 0x4b800000, v158
	v_cmp_gt_f32_e32 vcc, s67, v143
	v_cmp_gt_f32_e64 s[0:1], s67, v151
	v_cmp_gt_f32_e64 s[6:7], s67, v158
	v_mul_f32_e32 v163, 0x4b800000, v159
	v_cndmask_b32_e32 v143, v143, v160, vcc
	v_cndmask_b32_e64 v151, v151, v161, s[0:1]
	v_cndmask_b32_e64 v158, v158, v162, s[6:7]
	v_cmp_gt_f32_e64 s[8:9], s67, v159
	v_rsq_f32_e32 v143, v143
	v_rsq_f32_e32 v151, v151
	v_cndmask_b32_e64 v159, v159, v163, s[8:9]
	v_rsq_f32_e32 v161, v158
	v_rsq_f32_e32 v159, v159
	v_mul_f32_e32 v158, 0x45800000, v143
	v_mul_f32_e32 v160, 0x45800000, v151
	v_mul_f32_e32 v162, 0x45800000, v161
	v_mul_f32_e32 v163, 0x45800000, v159
	v_cndmask_b32_e32 v158, v143, v158, vcc
	v_cndmask_b32_e64 v160, v151, v160, s[0:1]
	v_cndmask_b32_e64 v162, v161, v162, s[6:7]
	v_pk_mul_f32 v[128:129], v[128:129], v[158:159] op_sel_hi:[1,0]
	v_pk_mul_f32 v[126:127], v[126:127], v[158:159] op_sel_hi:[1,0]
	v_pk_mul_f32 v[120:121], v[120:121], v[160:161] op_sel_hi:[1,0]
	v_pk_mul_f32 v[118:119], v[118:119], v[160:161] op_sel_hi:[1,0]
	v_pk_mul_f32 v[116:117], v[116:117], v[160:161] op_sel_hi:[1,0]
	v_pk_mul_f32 v[114:115], v[114:115], v[160:161] op_sel_hi:[1,0]
	v_pk_mul_f32 v[96:97], v[96:97], v[160:161] op_sel_hi:[1,0]
	v_pk_mul_f32 v[94:95], v[94:95], v[160:161] op_sel_hi:[1,0]
	v_pk_mul_f32 v[92:93], v[92:93], v[160:161] op_sel_hi:[1,0]
	v_pk_mul_f32 v[90:91], v[90:91], v[160:161] op_sel_hi:[1,0]
	v_pk_mul_f32 v[160:161], v[84:85], v[162:163] op_sel_hi:[1,0]
	v_cvt_pk_bf16_f32 v84, v126, v127
	v_cvt_pk_bf16_f32 v85, v128, v129
	v_cndmask_b32_e64 v164, v159, v163, s[8:9]
	v_pk_mul_f32 v[124:125], v[124:125], v[158:159] op_sel_hi:[1,0]
	v_pk_mul_f32 v[122:123], v[122:123], v[158:159] op_sel_hi:[1,0]
	v_pk_mul_f32 v[108:109], v[108:109], v[158:159] op_sel_hi:[1,0]
	v_pk_mul_f32 v[106:107], v[106:107], v[158:159] op_sel_hi:[1,0]
	v_pk_mul_f32 v[104:105], v[104:105], v[158:159] op_sel_hi:[1,0]
	v_pk_mul_f32 v[102:103], v[102:103], v[158:159] op_sel_hi:[1,0]
	v_pk_mul_f32 v[158:159], v[86:87], v[162:163] op_sel_hi:[1,0]
	v_cvt_pk_bf16_f32 v86, v122, v123
	v_cvt_pk_bf16_f32 v87, v124, v125
	global_store_dwordx4 v[156:157], v[84:87], off sc1
	v_pk_mul_f32 v[112:113], v[112:113], v[162:163] op_sel_hi:[1,0]
	v_pk_mul_f32 v[110:111], v[110:111], v[162:163] op_sel_hi:[1,0]
	v_cvt_pk_bf16_f32 v84, v106, v107
	v_cvt_pk_bf16_f32 v85, v108, v109
	v_cvt_pk_bf16_f32 v86, v102, v103
	v_cvt_pk_bf16_f32 v87, v104, v105
	global_store_dwordx4 v[156:157], v[84:87], off offset:256 sc1
	v_pk_mul_f32 v[100:101], v[100:101], v[162:163] op_sel_hi:[1,0]
	v_pk_mul_f32 v[98:99], v[98:99], v[162:163] op_sel_hi:[1,0]
	v_cvt_pk_bf16_f32 v84, v118, v119
	v_cvt_pk_bf16_f32 v85, v120, v121
	v_cvt_pk_bf16_f32 v86, v114, v115
	v_cvt_pk_bf16_f32 v87, v116, v117
	global_store_dwordx4 v[152:153], v[84:87], off sc1
	v_pk_mul_f32 v[88:89], v[88:89], v[162:163] op_sel_hi:[1,0]
	v_pk_mul_f32 v[80:81], v[80:81], v[164:165] op_sel_hi:[1,0]
	v_cvt_pk_bf16_f32 v84, v94, v95
	v_cvt_pk_bf16_f32 v85, v96, v97
	v_cvt_pk_bf16_f32 v86, v90, v91
	v_cvt_pk_bf16_f32 v87, v92, v93
	global_store_dwordx4 v[152:153], v[84:87], off offset:256 sc1
	v_pk_mul_f32 v[78:79], v[78:79], v[164:165] op_sel_hi:[1,0]
	v_pk_mul_f32 v[70:71], v[70:71], v[164:165] op_sel_hi:[1,0]
	v_cvt_pk_bf16_f32 v84, v110, v111
	v_cvt_pk_bf16_f32 v85, v112, v113
	v_cvt_pk_bf16_f32 v86, v98, v99
	v_cvt_pk_bf16_f32 v87, v100, v101
	global_store_dwordx4 v[154:155], v[84:87], off sc1
	v_pk_mul_f32 v[72:73], v[72:73], v[164:165] op_sel_hi:[1,0]
	s_nop 0
	v_pk_mul_f32 v[84:85], v[82:83], v[162:163] op_sel_hi:[1,0]
	v_cvt_pk_bf16_f32 v82, v158, v159
	v_cvt_pk_bf16_f32 v83, v88, v89
	s_nop 0
	v_cvt_pk_bf16_f32 v84, v84, v85
	v_cvt_pk_bf16_f32 v85, v160, v161
	global_store_dwordx4 v[154:155], v[82:85], off offset:256 sc1
	s_nop 1
	v_or_b32_e32 v82, 48, v142
	v_ashrrev_i32_e32 v83, 31, v82
	v_lshlrev_b64 v[82:83], 12, v[82:83]
	v_lshl_add_u64 v[82:83], s[16:17], 0, v[82:83]
	v_lshl_add_u64 v[82:83], v[82:83], 0, v[140:141]
	v_pk_mul_f32 v[84:85], v[76:77], v[164:165] op_sel_hi:[1,0]
	v_pk_mul_f32 v[76:77], v[74:75], v[164:165] op_sel_hi:[1,0]
	v_cvt_pk_bf16_f32 v74, v78, v79
	v_cvt_pk_bf16_f32 v75, v80, v81
	s_nop 0
	v_cvt_pk_bf16_f32 v76, v76, v77
	v_cvt_pk_bf16_f32 v77, v84, v85
	global_store_dwordx4 v[82:83], v[74:77], off sc1
	s_nop 1
	v_pk_mul_f32 v[74:75], v[68:69], v[164:165] op_sel_hi:[1,0]
	v_pk_mul_f32 v[68:69], v[66:67], v[164:165] op_sel_hi:[1,0]
	v_cvt_pk_bf16_f32 v66, v70, v71
	v_cvt_pk_bf16_f32 v67, v72, v73
	s_nop 0
	v_cvt_pk_bf16_f32 v68, v68, v69
	v_cvt_pk_bf16_f32 v69, v74, v75
	global_store_dwordx4 v[82:83], v[66:69], off offset:256 sc1
	s_nop 1
	v_add_u32_e32 v66, s27, v145
	v_ashrrev_i32_e32 v67, 31, v66
	v_lshlrev_b64 v[70:71], 12, v[66:67]
	v_or_b32_e32 v68, 16, v66
	v_ashrrev_i32_e32 v69, 31, v68
	v_lshl_add_u64 v[70:71], s[16:17], 0, v[70:71]
	v_lshlrev_b64 v[68:69], 12, v[68:69]
	v_lshl_add_u64 v[70:71], v[70:71], 0, v[140:141]
	v_lshl_add_u64 v[68:69], s[16:17], 0, v[68:69]
	v_lshl_add_u64 v[68:69], v[68:69], 0, v[140:141]
	s_waitcnt vmcnt(8)
	v_fmamk_f32 v67, v238, 0x3b800000, v150
	v_fmamk_f32 v72, v239, 0x3b800000, v150
	v_fmamk_f32 v73, v240, 0x3b800000, v150
	v_fmamk_f32 v74, v241, 0x3b800000, v150
	v_mul_f32_e32 v75, 0x4b800000, v67
	v_cmp_gt_f32_e32 vcc, s67, v67
	v_mul_f32_e32 v77, 0x4b800000, v73
	v_cmp_gt_f32_e64 s[6:7], s67, v73
	v_cndmask_b32_e32 v67, v67, v75, vcc
	v_mul_f32_e32 v76, 0x4b800000, v72
	v_cmp_gt_f32_e64 s[0:1], s67, v72
	v_cndmask_b32_e64 v73, v73, v77, s[6:7]
	v_rsq_f32_e32 v67, v67
	v_cndmask_b32_e64 v72, v72, v76, s[0:1]
	v_rsq_f32_e32 v73, v73
	v_rsq_f32_e32 v75, v72
	v_mul_f32_e32 v78, 0x4b800000, v74
	v_cmp_gt_f32_e64 s[8:9], s67, v74
	v_mul_f32_e32 v72, 0x45800000, v67
	v_mul_f32_e32 v76, 0x45800000, v73
	v_cndmask_b32_e64 v74, v74, v78, s[8:9]
	v_cndmask_b32_e32 v72, v67, v72, vcc
	v_rsq_f32_e32 v77, v74
	v_mul_f32_e32 v74, 0x45800000, v75
	v_cndmask_b32_e64 v76, v73, v76, s[6:7]
	v_pk_mul_f32 v[64:65], v[64:65], v[72:73] op_sel_hi:[1,0]
	v_pk_mul_f32 v[62:63], v[62:63], v[72:73] op_sel_hi:[1,0]
	v_pk_mul_f32 v[60:61], v[60:61], v[72:73] op_sel_hi:[1,0]
	v_pk_mul_f32 v[58:59], v[58:59], v[72:73] op_sel_hi:[1,0]
	v_pk_mul_f32 v[48:49], v[48:49], v[72:73] op_sel_hi:[1,0]
	v_pk_mul_f32 v[46:47], v[46:47], v[72:73] op_sel_hi:[1,0]
	v_pk_mul_f32 v[80:81], v[44:45], v[72:73] op_sel_hi:[1,0]
	v_pk_mul_f32 v[72:73], v[42:43], v[72:73] op_sel_hi:[1,0]
	v_cvt_pk_bf16_f32 v42, v62, v63
	v_cvt_pk_bf16_f32 v43, v64, v65
	v_cndmask_b32_e64 v74, v75, v74, s[0:1]
	v_cvt_pk_bf16_f32 v44, v58, v59
	v_cvt_pk_bf16_f32 v45, v60, v61
	global_store_dwordx4 v[70:71], v[42:45], off sc1
	v_pk_mul_f32 v[56:57], v[56:57], v[74:75] op_sel_hi:[1,0]
	v_pk_mul_f32 v[54:55], v[54:55], v[74:75] op_sel_hi:[1,0]
	v_cvt_pk_bf16_f32 v42, v46, v47
	v_cvt_pk_bf16_f32 v43, v48, v49
	v_cvt_pk_bf16_f32 v44, v72, v73
	v_cvt_pk_bf16_f32 v45, v80, v81
	global_store_dwordx4 v[70:71], v[42:45], off offset:256 sc1
	v_pk_mul_f32 v[52:53], v[52:53], v[74:75] op_sel_hi:[1,0]
	v_pk_mul_f32 v[50:51], v[50:51], v[74:75] op_sel_hi:[1,0]
	v_cvt_pk_bf16_f32 v42, v54, v55
	v_cvt_pk_bf16_f32 v43, v56, v57
	v_pk_mul_f32 v[38:39], v[38:39], v[74:75] op_sel_hi:[1,0]
	v_cvt_pk_bf16_f32 v44, v50, v51
	v_cvt_pk_bf16_f32 v45, v52, v53
	global_store_dwordx4 v[68:69], v[42:45], off sc1
	v_pk_mul_f32 v[40:41], v[40:41], v[74:75] op_sel_hi:[1,0]
	v_pk_mul_f32 v[32:33], v[32:33], v[76:77] op_sel_hi:[1,0]
	v_pk_mul_f32 v[42:43], v[36:37], v[74:75] op_sel_hi:[1,0]
	v_pk_mul_f32 v[36:37], v[34:35], v[74:75] op_sel_hi:[1,0]
	v_cvt_pk_bf16_f32 v34, v38, v39
	v_cvt_pk_bf16_f32 v35, v40, v41
	v_pk_mul_f32 v[30:31], v[30:31], v[76:77] op_sel_hi:[1,0]
	v_cvt_pk_bf16_f32 v36, v36, v37
	v_cvt_pk_bf16_f32 v37, v42, v43
	global_store_dwordx4 v[68:69], v[34:37], off offset:256 sc1
	v_pk_mul_f32 v[22:23], v[22:23], v[76:77] op_sel_hi:[1,0]
	v_pk_mul_f32 v[24:25], v[24:25], v[76:77] op_sel_hi:[1,0]
	v_or_b32_e32 v34, 32, v66
	v_ashrrev_i32_e32 v35, 31, v34
	v_lshlrev_b64 v[34:35], 12, v[34:35]
	v_lshl_add_u64 v[34:35], s[16:17], 0, v[34:35]
	v_lshl_add_u64 v[34:35], v[34:35], 0, v[140:141]
	v_pk_mul_f32 v[36:37], v[28:29], v[76:77] op_sel_hi:[1,0]
	v_pk_mul_f32 v[28:29], v[26:27], v[76:77] op_sel_hi:[1,0]
	v_cvt_pk_bf16_f32 v26, v30, v31
	v_cvt_pk_bf16_f32 v27, v32, v33
	v_mul_f32_e32 v78, 0x45800000, v77
	v_cvt_pk_bf16_f32 v28, v28, v29
	v_cvt_pk_bf16_f32 v29, v36, v37
	global_store_dwordx4 v[34:35], v[26:29], off sc1
	v_cndmask_b32_e64 v78, v77, v78, s[8:9]
	v_pk_mul_f32 v[16:17], v[16:17], v[78:79] op_sel_hi:[1,0]
	v_pk_mul_f32 v[26:27], v[20:21], v[76:77] op_sel_hi:[1,0]
	v_pk_mul_f32 v[20:21], v[18:19], v[76:77] op_sel_hi:[1,0]
	v_cvt_pk_bf16_f32 v18, v22, v23
	v_cvt_pk_bf16_f32 v19, v24, v25
	v_pk_mul_f32 v[14:15], v[14:15], v[78:79] op_sel_hi:[1,0]
	v_cvt_pk_bf16_f32 v20, v20, v21
	v_cvt_pk_bf16_f32 v21, v26, v27
	global_store_dwordx4 v[34:35], v[18:21], off offset:256 sc1
	v_pk_mul_f32 v[8:9], v[8:9], v[78:79] op_sel_hi:[1,0]
	v_pk_mul_f32 v[6:7], v[6:7], v[78:79] op_sel_hi:[1,0]
	v_or_b32_e32 v18, 48, v66
	v_ashrrev_i32_e32 v19, 31, v18
	v_lshlrev_b64 v[18:19], 12, v[18:19]
	v_lshl_add_u64 v[18:19], s[16:17], 0, v[18:19]
	v_lshl_add_u64 v[18:19], v[18:19], 0, v[140:141]
	v_pk_mul_f32 v[20:21], v[12:13], v[78:79] op_sel_hi:[1,0]
	v_pk_mul_f32 v[12:13], v[10:11], v[78:79] op_sel_hi:[1,0]
	v_cvt_pk_bf16_f32 v10, v14, v15
	v_cvt_pk_bf16_f32 v11, v16, v17
	s_andn2_b64 vcc, exec, s[30:31]
	v_cvt_pk_bf16_f32 v12, v12, v13
	v_cvt_pk_bf16_f32 v13, v20, v21
	global_store_dwordx4 v[18:19], v[10:13], off sc1
	s_mov_b64 s[0:1], -1
	s_nop 0
	v_pk_mul_f32 v[10:11], v[4:5], v[78:79] op_sel_hi:[1,0]
	v_pk_mul_f32 v[4:5], v[2:3], v[78:79] op_sel_hi:[1,0]
	v_cvt_pk_bf16_f32 v2, v6, v7
	v_cvt_pk_bf16_f32 v3, v8, v9
	s_nop 0
	v_cvt_pk_bf16_f32 v4, v4, v5
	v_cvt_pk_bf16_f32 v5, v10, v11
	global_store_dwordx4 v[18:19], v[2:5], off offset:256 sc1
	s_cbranch_vccnz .LBB0_1305
	s_andn2_b64 vcc, exec, s[14:15]
	s_cbranch_vccnz .LBB0_1304
	s_barrier
	s_branch .LBB0_1304

.LBB0_1343:
	ds_read_b128 v[144:147], v153
	ds_read_b128 v[158:161], v153 offset:1024
	ds_read_b128 v[162:165], v153 offset:2048
	ds_read_b128 v[166:169], v153 offset:3072
	ds_read_b128 v[170:173], v154
	ds_read_b128 v[174:177], v154 offset:1024
	ds_read_b128 v[178:181], v154 offset:2048
	ds_read_b128 v[184:187], v154 offset:3072
	s_add_u32 s6, s0, 0x100
	s_addc_u32 s7, s1, 0
	s_cmp_eq_u32 s52, 2
	s_cselect_b32 s27, s19, s7
	s_cselect_b32 s26, s18, s6
	s_cselect_b32 s9, s25, s51
	s_cselect_b32 s8, s24, s50
	v_lshl_add_u64 v[148:149], s[0:1], 0, v[138:139]
	s_add_i32 m0, s34, 0xc000
	ds_read_b128 v[188:191], v155
	ds_read_b128 v[192:195], v155 offset:1024
	ds_read_b128 v[196:199], v155 offset:2048
	ds_read_b128 v[200:203], v155 offset:3072
	ds_read_b128 v[204:207], v155 offset:4096
	ds_read_b128 v[208:211], v155 offset:5120
	ds_read_b128 v[212:215], v155 offset:6144
	ds_read_b128 v[216:219], v155 offset:7168
	global_load_lds_dwordx4 v[148:149], off
	v_lshl_add_u64 v[148:149], s[0:1], 0, v[140:141]
	s_add_i32 m0, s34, 0xe000
	s_nop 0
	global_load_lds_dwordx4 v[148:149], off
	s_waitcnt vmcnt(8)
	s_waitcnt lgkmcnt(0)
	s_barrier
	s_setprio 1
	s_waitcnt lgkmcnt(0)
	v_mfma_f32_16x16x32_bf16 v[126:129], v[144:147], v[188:191], v[126:129]
	v_mfma_f32_16x16x32_bf16 v[122:125], v[162:165], v[188:191], v[122:125]
	v_mfma_f32_16x16x32_bf16 v[118:121], v[144:147], v[196:199], v[118:121]
	v_mfma_f32_16x16x32_bf16 v[114:117], v[162:165], v[196:199], v[114:117]
	v_mfma_f32_16x16x32_bf16 v[110:113], v[144:147], v[204:207], v[110:113]
	v_mfma_f32_16x16x32_bf16 v[98:101], v[162:165], v[204:207], v[98:101]
	v_mfma_f32_16x16x32_bf16 v[82:85], v[144:147], v[212:215], v[82:85]
	v_mfma_f32_16x16x32_bf16 v[74:77], v[162:165], v[212:215], v[74:77]
	v_mfma_f32_16x16x32_bf16 v[126:129], v[158:161], v[192:195], v[126:129]
	v_mfma_f32_16x16x32_bf16 v[122:125], v[166:169], v[192:195], v[122:125]
	v_mfma_f32_16x16x32_bf16 v[118:121], v[158:161], v[200:203], v[118:121]
	v_mfma_f32_16x16x32_bf16 v[114:117], v[166:169], v[200:203], v[114:117]
	v_mfma_f32_16x16x32_bf16 v[110:113], v[158:161], v[208:211], v[110:113]
	v_mfma_f32_16x16x32_bf16 v[98:101], v[166:169], v[208:211], v[98:101]
	v_mfma_f32_16x16x32_bf16 v[82:85], v[158:161], v[216:219], v[82:85]
	v_mfma_f32_16x16x32_bf16 v[74:77], v[166:169], v[216:219], v[74:77]
	s_setprio 0
	s_setprio 1
	v_mfma_f32_16x16x32_bf16 v[106:109], v[170:173], v[188:191], v[106:109]
	v_mfma_f32_16x16x32_bf16 v[102:105], v[178:181], v[188:191], v[102:105]
	v_mfma_f32_16x16x32_bf16 v[94:97], v[170:173], v[196:199], v[94:97]
	v_mfma_f32_16x16x32_bf16 v[90:93], v[178:181], v[196:199], v[90:93]
	v_mfma_f32_16x16x32_bf16 v[86:89], v[170:173], v[204:207], v[86:89]
	v_mfma_f32_16x16x32_bf16 v[78:81], v[178:181], v[204:207], v[78:81]
	v_mfma_f32_16x16x32_bf16 v[70:73], v[170:173], v[212:215], v[70:73]
	v_mfma_f32_16x16x32_bf16 v[66:69], v[178:181], v[212:215], v[66:69]
	v_mfma_f32_16x16x32_bf16 v[106:109], v[174:177], v[192:195], v[106:109]
	v_mfma_f32_16x16x32_bf16 v[102:105], v[184:187], v[192:195], v[102:105]
	v_mfma_f32_16x16x32_bf16 v[94:97], v[174:177], v[200:203], v[94:97]
	v_mfma_f32_16x16x32_bf16 v[90:93], v[184:187], v[200:203], v[90:93]
	v_mfma_f32_16x16x32_bf16 v[86:89], v[174:177], v[208:211], v[86:89]
	v_mfma_f32_16x16x32_bf16 v[78:81], v[184:187], v[208:211], v[78:81]
	v_mfma_f32_16x16x32_bf16 v[70:73], v[174:177], v[216:219], v[70:73]
	v_mfma_f32_16x16x32_bf16 v[66:69], v[184:187], v[216:219], v[66:69]
	s_setprio 0
	s_barrier
	s_add_i32 s0, s42, s5
	v_lshl_add_u64 v[148:149], s[8:9], 0, v[132:133]
	s_mov_b32 m0, s0
	ds_read_b128 v[188:191], v155 offset:16384
	ds_read_b128 v[192:195], v155 offset:17408
	ds_read_b128 v[196:199], v155 offset:18432
	ds_read_b128 v[200:203], v155 offset:19456
	ds_read_b128 v[204:207], v155 offset:20480
	ds_read_b128 v[208:211], v155 offset:21504
	ds_read_b128 v[212:215], v155 offset:22528
	ds_read_b128 v[216:219], v155 offset:23552
	global_load_lds_dwordx4 v[148:149], off
	s_add_i32 m0, s0, 0x2000
	s_add_u32 s0, s8, 0x18000
	v_lshl_add_u64 v[220:221], s[8:9], 0, v[136:137]
	s_addc_u32 s1, s9, 0
	s_add_i32 s53, s43, s5
	global_load_lds_dwordx4 v[220:221], off
	v_lshl_add_u64 v[222:223], s[0:1], 0, v[132:133]
	s_mov_b32 m0, s53
	v_lshl_add_u64 v[224:225], s[26:27], 0, v[134:135]
	global_load_lds_dwordx4 v[222:223], off
	v_lshl_add_u64 v[222:223], s[0:1], 0, v[136:137]
	s_add_i32 m0, s53, 0x2000
	s_nop 0
	global_load_lds_dwordx4 v[222:223], off
	v_lshl_add_u64 v[222:223], s[26:27], 0, v[130:131]
	s_mov_b32 m0, s34
	s_nop 0
	global_load_lds_dwordx4 v[222:223], off
	s_mov_b32 m0, s35
	s_nop 0
	global_load_lds_dwordx4 v[224:225], off
	s_waitcnt vmcnt(8)
	s_waitcnt lgkmcnt(0)
	s_barrier
	s_setprio 1
	s_waitcnt lgkmcnt(0)
	v_mfma_f32_16x16x32_bf16 v[62:65], v[144:147], v[188:191], v[62:65]
	v_mfma_f32_16x16x32_bf16 v[58:61], v[162:165], v[188:191], v[58:61]
	v_mfma_f32_16x16x32_bf16 v[54:57], v[144:147], v[196:199], v[54:57]
	v_mfma_f32_16x16x32_bf16 v[46:49], v[162:165], v[196:199], v[46:49]
	v_mfma_f32_16x16x32_bf16 v[34:37], v[144:147], v[204:207], v[34:37]
	v_mfma_f32_16x16x32_bf16 v[26:29], v[162:165], v[204:207], v[26:29]
	v_mfma_f32_16x16x32_bf16 v[18:21], v[144:147], v[212:215], v[18:21]
	v_mfma_f32_16x16x32_bf16 v[10:13], v[162:165], v[212:215], v[10:13]
	v_mfma_f32_16x16x32_bf16 v[62:65], v[158:161], v[192:195], v[62:65]
	v_mfma_f32_16x16x32_bf16 v[58:61], v[166:169], v[192:195], v[58:61]
	v_mfma_f32_16x16x32_bf16 v[54:57], v[158:161], v[200:203], v[54:57]
	v_mfma_f32_16x16x32_bf16 v[46:49], v[166:169], v[200:203], v[46:49]
	v_mfma_f32_16x16x32_bf16 v[34:37], v[158:161], v[208:211], v[34:37]
	v_mfma_f32_16x16x32_bf16 v[26:29], v[166:169], v[208:211], v[26:29]
	v_mfma_f32_16x16x32_bf16 v[18:21], v[158:161], v[216:219], v[18:21]
	v_mfma_f32_16x16x32_bf16 v[10:13], v[166:169], v[216:219], v[10:13]
	s_setprio 0
	s_setprio 1
	v_mfma_f32_16x16x32_bf16 v[50:53], v[170:173], v[188:191], v[50:53]
	v_mfma_f32_16x16x32_bf16 v[42:45], v[178:181], v[188:191], v[42:45]
	v_mfma_f32_16x16x32_bf16 v[38:41], v[170:173], v[196:199], v[38:41]
	v_mfma_f32_16x16x32_bf16 v[30:33], v[178:181], v[196:199], v[30:33]
	v_mfma_f32_16x16x32_bf16 v[22:25], v[170:173], v[204:207], v[22:25]
	v_mfma_f32_16x16x32_bf16 v[14:17], v[178:181], v[204:207], v[14:17]
	v_mfma_f32_16x16x32_bf16 v[6:9], v[170:173], v[212:215], v[6:9]
	v_mfma_f32_16x16x32_bf16 v[2:5], v[178:181], v[212:215], v[2:5]
	v_mfma_f32_16x16x32_bf16 v[50:53], v[174:177], v[192:195], v[50:53]
	v_mfma_f32_16x16x32_bf16 v[42:45], v[184:187], v[192:195], v[42:45]
	v_mfma_f32_16x16x32_bf16 v[38:41], v[174:177], v[200:203], v[38:41]
	v_mfma_f32_16x16x32_bf16 v[30:33], v[184:187], v[200:203], v[30:33]
	v_mfma_f32_16x16x32_bf16 v[22:25], v[174:177], v[208:211], v[22:25]
	v_mfma_f32_16x16x32_bf16 v[14:17], v[184:187], v[208:211], v[14:17]
	v_mfma_f32_16x16x32_bf16 v[6:9], v[174:177], v[216:219], v[6:9]
	v_mfma_f32_16x16x32_bf16 v[2:5], v[184:187], v[216:219], v[2:5]
	s_setprio 0
	s_barrier
	s_add_i32 s53, 0, 0x18000
	v_add_u32_e32 v157, s53, v150
	s_add_i32 s54, 0, 0x1c000
	ds_read_b128 v[144:147], v157
	ds_read_b128 v[158:161], v157 offset:1024
	ds_read_b128 v[162:165], v157 offset:2048
	ds_read_b128 v[166:169], v157 offset:3072
	v_add_u32_e32 v157, s54, v150
	ds_read_b128 v[170:173], v157
	ds_read_b128 v[174:177], v157 offset:1024
	ds_read_b128 v[178:181], v157 offset:2048
	ds_read_b128 v[184:187], v157 offset:3072
	s_add_u32 s0, s26, 0x18000
	s_addc_u32 s1, s27, 0
	s_mov_b32 m0, s36
	v_lshl_add_u64 v[226:227], s[0:1], 0, v[130:131]
	ds_read_b128 v[188:191], v155 offset:32768
	ds_read_b128 v[192:195], v155 offset:33792
	ds_read_b128 v[196:199], v155 offset:34816
	ds_read_b128 v[200:203], v155 offset:35840
	ds_read_b128 v[204:207], v155 offset:36864
	ds_read_b128 v[208:211], v155 offset:37888
	ds_read_b128 v[212:215], v155 offset:38912
	ds_read_b128 v[216:219], v155 offset:39936
	global_load_lds_dwordx4 v[226:227], off
	v_lshl_add_u64 v[226:227], s[0:1], 0, v[134:135]
	s_mov_b32 m0, s37
	s_nop 0
	global_load_lds_dwordx4 v[226:227], off
	s_waitcnt vmcnt(8)
	s_waitcnt lgkmcnt(0)
	s_barrier
	s_setprio 1
	s_waitcnt lgkmcnt(0)
	v_mfma_f32_16x16x32_bf16 v[126:129], v[144:147], v[188:191], v[126:129]
	v_mfma_f32_16x16x32_bf16 v[122:125], v[162:165], v[188:191], v[122:125]
	v_mfma_f32_16x16x32_bf16 v[118:121], v[144:147], v[196:199], v[118:121]
	v_mfma_f32_16x16x32_bf16 v[114:117], v[162:165], v[196:199], v[114:117]
	v_mfma_f32_16x16x32_bf16 v[110:113], v[144:147], v[204:207], v[110:113]
	v_mfma_f32_16x16x32_bf16 v[98:101], v[162:165], v[204:207], v[98:101]
	v_mfma_f32_16x16x32_bf16 v[82:85], v[144:147], v[212:215], v[82:85]
	v_mfma_f32_16x16x32_bf16 v[74:77], v[162:165], v[212:215], v[74:77]
	v_mfma_f32_16x16x32_bf16 v[126:129], v[158:161], v[192:195], v[126:129]
	v_mfma_f32_16x16x32_bf16 v[122:125], v[166:169], v[192:195], v[122:125]
	v_mfma_f32_16x16x32_bf16 v[118:121], v[158:161], v[200:203], v[118:121]
	v_mfma_f32_16x16x32_bf16 v[114:117], v[166:169], v[200:203], v[114:117]
	v_mfma_f32_16x16x32_bf16 v[110:113], v[158:161], v[208:211], v[110:113]
	v_mfma_f32_16x16x32_bf16 v[98:101], v[166:169], v[208:211], v[98:101]
	v_mfma_f32_16x16x32_bf16 v[82:85], v[158:161], v[216:219], v[82:85]
	v_mfma_f32_16x16x32_bf16 v[74:77], v[166:169], v[216:219], v[74:77]
	s_setprio 0
	s_setprio 1
	v_mfma_f32_16x16x32_bf16 v[106:109], v[170:173], v[188:191], v[106:109]
	v_mfma_f32_16x16x32_bf16 v[102:105], v[178:181], v[188:191], v[102:105]
	v_mfma_f32_16x16x32_bf16 v[94:97], v[170:173], v[196:199], v[94:97]
	v_mfma_f32_16x16x32_bf16 v[90:93], v[178:181], v[196:199], v[90:93]
	v_mfma_f32_16x16x32_bf16 v[86:89], v[170:173], v[204:207], v[86:89]
	v_mfma_f32_16x16x32_bf16 v[78:81], v[178:181], v[204:207], v[78:81]
	v_mfma_f32_16x16x32_bf16 v[70:73], v[170:173], v[212:215], v[70:73]
	v_mfma_f32_16x16x32_bf16 v[66:69], v[178:181], v[212:215], v[66:69]
	v_mfma_f32_16x16x32_bf16 v[106:109], v[174:177], v[192:195], v[106:109]
	v_mfma_f32_16x16x32_bf16 v[102:105], v[184:187], v[192:195], v[102:105]
	v_mfma_f32_16x16x32_bf16 v[94:97], v[174:177], v[200:203], v[94:97]
	v_mfma_f32_16x16x32_bf16 v[90:93], v[184:187], v[200:203], v[90:93]
	v_mfma_f32_16x16x32_bf16 v[86:89], v[174:177], v[208:211], v[86:89]
	v_mfma_f32_16x16x32_bf16 v[78:81], v[184:187], v[208:211], v[78:81]
	v_mfma_f32_16x16x32_bf16 v[70:73], v[174:177], v[216:219], v[70:73]
	v_mfma_f32_16x16x32_bf16 v[66:69], v[184:187], v[216:219], v[66:69]
	s_setprio 0
	s_barrier
	s_add_i32 s0, s53, s5
	v_lshl_add_u64 v[148:149], v[148:149], 0, s[16:17]
	s_mov_b32 m0, s0
	ds_read_b128 v[188:191], v155 offset:49152
	ds_read_b128 v[192:195], v155 offset:50176
	ds_read_b128 v[196:199], v155 offset:51200
	ds_read_b128 v[200:203], v155 offset:52224
	ds_read_b128 v[204:207], v155 offset:53248
	ds_read_b128 v[208:211], v155 offset:54272
	ds_read_b128 v[212:215], v155 offset:55296
	ds_read_b128 v[216:219], v155 offset:56320
	global_load_lds_dwordx4 v[148:149], off
	s_add_i32 m0, s0, 0x2000
	s_add_u32 s0, s8, 0x18080
	v_lshl_add_u64 v[148:149], v[220:221], 0, s[16:17]
	s_addc_u32 s1, s9, 0
	s_add_i32 s8, s54, s5
	global_load_lds_dwordx4 v[148:149], off
	v_lshl_add_u64 v[148:149], s[0:1], 0, v[132:133]
	s_mov_b32 m0, s8
	s_nop 0
	global_load_lds_dwordx4 v[148:149], off
	v_lshl_add_u64 v[148:149], s[0:1], 0, v[136:137]
	s_add_i32 m0, s8, 0x2000
	s_nop 0
	global_load_lds_dwordx4 v[148:149], off
	v_lshl_add_u64 v[148:149], v[222:223], 0, s[16:17]
	s_mov_b32 m0, s40
	s_nop 0
	global_load_lds_dwordx4 v[148:149], off
	v_lshl_add_u64 v[148:149], v[224:225], 0, s[16:17]
	s_mov_b32 m0, s41
	s_nop 0
	global_load_lds_dwordx4 v[148:149], off
	s_waitcnt vmcnt(8)
	s_waitcnt lgkmcnt(0)
	s_barrier
	s_setprio 1
	s_waitcnt lgkmcnt(0)
	v_mfma_f32_16x16x32_bf16 v[62:65], v[144:147], v[188:191], v[62:65]
	v_mfma_f32_16x16x32_bf16 v[58:61], v[162:165], v[188:191], v[58:61]
	v_mfma_f32_16x16x32_bf16 v[54:57], v[144:147], v[196:199], v[54:57]
	v_mfma_f32_16x16x32_bf16 v[46:49], v[162:165], v[196:199], v[46:49]
	v_mfma_f32_16x16x32_bf16 v[34:37], v[144:147], v[204:207], v[34:37]
	v_mfma_f32_16x16x32_bf16 v[26:29], v[162:165], v[204:207], v[26:29]
	v_mfma_f32_16x16x32_bf16 v[18:21], v[144:147], v[212:215], v[18:21]
	v_mfma_f32_16x16x32_bf16 v[10:13], v[162:165], v[212:215], v[10:13]
	v_mfma_f32_16x16x32_bf16 v[62:65], v[158:161], v[192:195], v[62:65]
	v_mfma_f32_16x16x32_bf16 v[58:61], v[166:169], v[192:195], v[58:61]
	v_mfma_f32_16x16x32_bf16 v[54:57], v[158:161], v[200:203], v[54:57]
	v_mfma_f32_16x16x32_bf16 v[46:49], v[166:169], v[200:203], v[46:49]
	v_mfma_f32_16x16x32_bf16 v[34:37], v[158:161], v[208:211], v[34:37]
	v_mfma_f32_16x16x32_bf16 v[26:29], v[166:169], v[208:211], v[26:29]
	v_mfma_f32_16x16x32_bf16 v[18:21], v[158:161], v[216:219], v[18:21]
	v_mfma_f32_16x16x32_bf16 v[10:13], v[166:169], v[216:219], v[10:13]
	s_setprio 0
	s_setprio 1
	v_mfma_f32_16x16x32_bf16 v[50:53], v[170:173], v[188:191], v[50:53]
	v_mfma_f32_16x16x32_bf16 v[42:45], v[178:181], v[188:191], v[42:45]
	v_mfma_f32_16x16x32_bf16 v[38:41], v[170:173], v[196:199], v[38:41]
	v_mfma_f32_16x16x32_bf16 v[30:33], v[178:181], v[196:199], v[30:33]
	v_mfma_f32_16x16x32_bf16 v[22:25], v[170:173], v[204:207], v[22:25]
	v_mfma_f32_16x16x32_bf16 v[14:17], v[178:181], v[204:207], v[14:17]
	v_mfma_f32_16x16x32_bf16 v[6:9], v[170:173], v[212:215], v[6:9]
	v_mfma_f32_16x16x32_bf16 v[2:5], v[178:181], v[212:215], v[2:5]
	v_mfma_f32_16x16x32_bf16 v[50:53], v[174:177], v[192:195], v[50:53]
	v_mfma_f32_16x16x32_bf16 v[42:45], v[184:187], v[192:195], v[42:45]
	v_mfma_f32_16x16x32_bf16 v[38:41], v[174:177], v[200:203], v[38:41]
	v_mfma_f32_16x16x32_bf16 v[30:33], v[184:187], v[200:203], v[30:33]
	v_mfma_f32_16x16x32_bf16 v[22:25], v[174:177], v[208:211], v[22:25]
	v_mfma_f32_16x16x32_bf16 v[14:17], v[184:187], v[208:211], v[14:17]
	v_mfma_f32_16x16x32_bf16 v[6:9], v[174:177], v[216:219], v[6:9]
	v_mfma_f32_16x16x32_bf16 v[2:5], v[184:187], v[216:219], v[2:5]
	s_setprio 0
	s_barrier
	s_add_i32 s52, s52, 2
	s_add_u32 s50, s50, 0x100
	s_addc_u32 s51, s51, 0
	s_cmp_gt_u32 s52, 3
	s_mov_b64 s[0:1], s[6:7]
	s_cbranch_scc0 .LBB0_1343
	s_lshl_b32 s26, s49, 8
	s_add_i32 s26, s26, s39
	v_or_b32_e32 v148, s26, v1
	v_ashrrev_i32_e32 v149, 31, v148
	v_lshl_add_u64 v[144:145], v[148:149], 2, s[14:15]
	global_load_dword v149, v[144:145], off
	global_load_dword v157, v[144:145], off offset:64
	global_load_dword v164, v[144:145], off offset:128
	global_load_dword v165, v[144:145], off offset:192
	v_add_u32_e32 v246, s26, v151
	v_ashrrev_i32_e32 v247, 31, v246
	v_lshl_add_u64 v[246:247], v[246:247], 2, s[14:15]
	global_load_dword v238, v[246:247], off
	global_load_dword v239, v[246:247], off offset:64
	global_load_dword v240, v[246:247], off offset:128
	global_load_dword v241, v[246:247], off offset:192
	v_mov_b64_e32 v[144:145], s[12:13]
	v_or_b32_e32 v160, 16, v148
	v_or_b32_e32 v162, 32, v148
	v_mad_i64_i32 v[158:159], s[0:1], v148, s45, v[144:145]
	v_mad_i64_i32 v[160:161], s[0:1], v160, s45, v[144:145]
	v_mad_i64_i32 v[162:163], s[0:1], v162, s45, v[144:145]
	v_lshl_or_b32 v146, s48, 8, v152
	v_ashrrev_i32_e32 v147, 31, v146
	v_lshlrev_b64 v[146:147], 1, v[146:147]
	v_lshl_add_u64 v[158:159], v[158:159], 0, v[146:147]
	v_lshl_add_u64 v[160:161], v[160:161], 0, v[146:147]
	v_lshl_add_u64 v[162:163], v[162:163], 0, v[146:147]
	s_mov_b32 s48, s46
	s_mov_b32 s49, s47
	s_waitcnt vmcnt(4)
	v_fmamk_f32 v149, v149, 0x3b2aaaab, v156
	v_fmamk_f32 v157, v157, 0x3b2aaaab, v156
	v_fmamk_f32 v164, v164, 0x3b2aaaab, v156
	v_fmamk_f32 v165, v165, 0x3b2aaaab, v156
	v_mul_f32_e32 v166, 0x4b800000, v149
	v_mul_f32_e32 v167, 0x4b800000, v157
	v_mul_f32_e32 v168, 0x4b800000, v164
	v_cmp_gt_f32_e32 vcc, s44, v149
	v_cmp_gt_f32_e64 s[0:1], s44, v157
	v_cmp_gt_f32_e64 s[6:7], s44, v164
	v_mul_f32_e32 v169, 0x4b800000, v165
	v_cndmask_b32_e32 v149, v149, v166, vcc
	v_cndmask_b32_e64 v157, v157, v167, s[0:1]
	v_cndmask_b32_e64 v164, v164, v168, s[6:7]
	v_cmp_gt_f32_e64 s[8:9], s44, v165
	v_rsq_f32_e32 v149, v149
	v_rsq_f32_e32 v157, v157
	v_cndmask_b32_e64 v165, v165, v169, s[8:9]
	v_rsq_f32_e32 v164, v164
	v_rsq_f32_e32 v165, v165
	v_mul_f32_e32 v166, 0x45800000, v149
	v_mul_f32_e32 v167, 0x45800000, v157
	v_mul_f32_e32 v168, 0x45800000, v164
	v_mul_f32_e32 v169, 0x45800000, v165
	v_cndmask_b32_e32 v149, v149, v166, vcc
	v_cndmask_b32_e64 v157, v157, v167, s[0:1]
	v_cndmask_b32_e64 v167, v164, v168, s[6:7]
	v_cndmask_b32_e64 v165, v165, v169, s[8:9]
	v_mul_f32_e32 v164, 0x3dd53b94, v149
	v_mul_f32_e32 v166, 0x3dd53b94, v157
	v_mul_f32_e32 v168, 0x3dd53b94, v167
	v_mul_f32_e32 v170, 0x3dd53b94, v165
	v_pk_mul_f32 v[128:129], v[128:129], v[164:165] op_sel_hi:[1,0]
	v_pk_mul_f32 v[126:127], v[126:127], v[164:165] op_sel_hi:[1,0]
	v_pk_mul_f32 v[124:125], v[124:125], v[164:165] op_sel_hi:[1,0]
	v_pk_mul_f32 v[122:123], v[122:123], v[164:165] op_sel_hi:[1,0]
	v_pk_mul_f32 v[108:109], v[108:109], v[164:165] op_sel_hi:[1,0]
	v_pk_mul_f32 v[106:107], v[106:107], v[164:165] op_sel_hi:[1,0]
	v_pk_mul_f32 v[104:105], v[104:105], v[164:165] op_sel_hi:[1,0]
	v_pk_mul_f32 v[102:103], v[102:103], v[164:165] op_sel_hi:[1,0]
	v_pk_mul_f32 v[120:121], v[120:121], v[166:167] op_sel_hi:[1,0]
	v_pk_mul_f32 v[118:119], v[118:119], v[166:167] op_sel_hi:[1,0]
	v_pk_mul_f32 v[116:117], v[116:117], v[166:167] op_sel_hi:[1,0]
	v_pk_mul_f32 v[114:115], v[114:115], v[166:167] op_sel_hi:[1,0]
	v_pk_mul_f32 v[96:97], v[96:97], v[166:167] op_sel_hi:[1,0]
	v_pk_mul_f32 v[94:95], v[94:95], v[166:167] op_sel_hi:[1,0]
	v_pk_mul_f32 v[92:93], v[92:93], v[166:167] op_sel_hi:[1,0]
	v_pk_mul_f32 v[164:165], v[90:91], v[166:167] op_sel_hi:[1,0]
	v_pk_mul_f32 v[166:167], v[88:89], v[168:169] op_sel_hi:[1,0]
	v_cvt_pk_bf16_f32 v88, v126, v127
	v_cvt_pk_bf16_f32 v89, v128, v129
	v_cvt_pk_bf16_f32 v90, v122, v123
	v_cvt_pk_bf16_f32 v91, v124, v125
	global_store_dwordx4 v[158:159], v[88:91], off sc1
	v_pk_mul_f32 v[112:113], v[112:113], v[168:169] op_sel_hi:[1,0]
	v_pk_mul_f32 v[110:111], v[110:111], v[168:169] op_sel_hi:[1,0]
	v_cvt_pk_bf16_f32 v88, v106, v107
	v_cvt_pk_bf16_f32 v89, v108, v109
	v_cvt_pk_bf16_f32 v90, v102, v103
	v_cvt_pk_bf16_f32 v91, v104, v105
	global_store_dwordx4 v[158:159], v[88:91], off offset:256 sc1
	v_pk_mul_f32 v[100:101], v[100:101], v[168:169] op_sel_hi:[1,0]
	v_pk_mul_f32 v[98:99], v[98:99], v[168:169] op_sel_hi:[1,0]
	v_cvt_pk_bf16_f32 v88, v118, v119
	v_cvt_pk_bf16_f32 v89, v120, v121
	v_cvt_pk_bf16_f32 v90, v114, v115
	v_cvt_pk_bf16_f32 v91, v116, v117
	global_store_dwordx4 v[160:161], v[88:91], off sc1
	v_pk_mul_f32 v[86:87], v[86:87], v[168:169] op_sel_hi:[1,0]
	v_pk_mul_f32 v[82:83], v[82:83], v[170:171] op_sel_hi:[1,0]
	v_cvt_pk_bf16_f32 v88, v94, v95
	v_cvt_pk_bf16_f32 v89, v96, v97
	v_cvt_pk_bf16_f32 v90, v164, v165
	v_cvt_pk_bf16_f32 v91, v92, v93
	global_store_dwordx4 v[160:161], v[88:91], off offset:256 sc1
	v_pk_mul_f32 v[70:71], v[70:71], v[170:171] op_sel_hi:[1,0]
	v_pk_mul_f32 v[72:73], v[72:73], v[170:171] op_sel_hi:[1,0]
	v_cvt_pk_bf16_f32 v88, v110, v111
	v_cvt_pk_bf16_f32 v89, v112, v113
	v_cvt_pk_bf16_f32 v90, v98, v99
	v_cvt_pk_bf16_f32 v91, v100, v101
	global_store_dwordx4 v[162:163], v[88:91], off sc1
	s_nop 1
	v_pk_mul_f32 v[88:89], v[80:81], v[168:169] op_sel_hi:[1,0]
	v_pk_mul_f32 v[80:81], v[78:79], v[168:169] op_sel_hi:[1,0]
	v_cvt_pk_bf16_f32 v78, v86, v87
	v_cvt_pk_bf16_f32 v79, v166, v167
	s_nop 0
	v_cvt_pk_bf16_f32 v80, v80, v81
	v_cvt_pk_bf16_f32 v81, v88, v89
	global_store_dwordx4 v[162:163], v[78:81], off offset:256 sc1
	s_nop 1
	v_or_b32_e32 v78, 48, v148
	v_mad_i64_i32 v[78:79], s[0:1], v78, s45, v[144:145]
	v_lshl_add_u64 v[78:79], v[78:79], 0, v[146:147]
	v_pk_mul_f32 v[80:81], v[84:85], v[170:171] op_sel_hi:[1,0]
	v_pk_mul_f32 v[84:85], v[76:77], v[170:171] op_sel_hi:[1,0]
	v_pk_mul_f32 v[76:77], v[74:75], v[170:171] op_sel_hi:[1,0]
	v_cvt_pk_bf16_f32 v74, v82, v83
	v_cvt_pk_bf16_f32 v75, v80, v81
	s_nop 0
	v_cvt_pk_bf16_f32 v76, v76, v77
	v_cvt_pk_bf16_f32 v77, v84, v85
	global_store_dwordx4 v[78:79], v[74:77], off sc1
	s_nop 1
	v_pk_mul_f32 v[74:75], v[68:69], v[170:171] op_sel_hi:[1,0]
	v_pk_mul_f32 v[68:69], v[66:67], v[170:171] op_sel_hi:[1,0]
	v_cvt_pk_bf16_f32 v66, v70, v71
	v_cvt_pk_bf16_f32 v67, v72, v73
	s_nop 0
	v_cvt_pk_bf16_f32 v68, v68, v69
	v_cvt_pk_bf16_f32 v69, v74, v75
	global_store_dwordx4 v[78:79], v[66:69], off offset:256 sc1
	s_nop 1
	v_add_u32_e32 v66, s26, v151
	v_ashrrev_i32_e32 v67, 31, v66
	v_or_b32_e32 v70, 16, v66
	v_mad_i64_i32 v[68:69], s[0:1], v66, s45, v[144:145]
	v_mad_i64_i32 v[70:71], s[0:1], v70, s45, v[144:145]
	v_lshl_add_u64 v[68:69], v[68:69], 0, v[146:147]
	v_lshl_add_u64 v[70:71], v[70:71], 0, v[146:147]
	s_waitcnt vmcnt(8)
	v_fmamk_f32 v67, v238, 0x3b2aaaab, v156
	v_fmamk_f32 v72, v239, 0x3b2aaaab, v156
	v_fmamk_f32 v73, v240, 0x3b2aaaab, v156
	v_mul_f32_e32 v75, 0x4b800000, v67
	v_cmp_gt_f32_e32 vcc, s44, v67
	v_mul_f32_e32 v76, 0x4b800000, v72
	v_mul_f32_e32 v77, 0x4b800000, v73
	v_cndmask_b32_e32 v67, v67, v75, vcc
	v_cmp_gt_f32_e64 s[0:1], s44, v72
	v_cmp_gt_f32_e64 s[6:7], s44, v73
	v_fmamk_f32 v74, v241, 0x3b2aaaab, v156
	v_cndmask_b32_e64 v72, v72, v76, s[0:1]
	v_cndmask_b32_e64 v73, v73, v77, s[6:7]
	v_rsq_f32_e32 v67, v67
	v_mul_f32_e32 v78, 0x4b800000, v74
	v_cmp_gt_f32_e64 s[8:9], s44, v74
	v_rsq_f32_e32 v72, v72
	v_rsq_f32_e32 v73, v73
	v_cndmask_b32_e64 v74, v74, v78, s[8:9]
	v_rsq_f32_e32 v74, v74
	v_mul_f32_e32 v75, 0x45800000, v67
	v_mul_f32_e32 v76, 0x45800000, v72
	v_mul_f32_e32 v77, 0x45800000, v73
	v_cndmask_b32_e32 v67, v67, v75, vcc
	v_cndmask_b32_e64 v75, v72, v76, s[0:1]
	v_cndmask_b32_e64 v73, v73, v77, s[6:7]
	v_mul_f32_e32 v72, 0x3dd53b94, v67
	v_mul_f32_e32 v78, 0x45800000, v74
	v_mul_f32_e32 v76, 0x3dd53b94, v73
	v_pk_mul_f32 v[64:65], v[64:65], v[72:73] op_sel_hi:[1,0]
	v_pk_mul_f32 v[62:63], v[62:63], v[72:73] op_sel_hi:[1,0]
	v_pk_mul_f32 v[60:61], v[60:61], v[72:73] op_sel_hi:[1,0]
	v_pk_mul_f32 v[58:59], v[58:59], v[72:73] op_sel_hi:[1,0]
	v_pk_mul_f32 v[52:53], v[52:53], v[72:73] op_sel_hi:[1,0]
	v_pk_mul_f32 v[50:51], v[50:51], v[72:73] op_sel_hi:[1,0]
	v_pk_mul_f32 v[80:81], v[44:45], v[72:73] op_sel_hi:[1,0]
	v_pk_mul_f32 v[72:73], v[42:43], v[72:73] op_sel_hi:[1,0]
	v_cvt_pk_bf16_f32 v42, v62, v63
	v_cvt_pk_bf16_f32 v43, v64, v65
	v_cvt_pk_bf16_f32 v44, v58, v59
	v_cvt_pk_bf16_f32 v45, v60, v61
	v_cndmask_b32_e64 v77, v74, v78, s[8:9]
	v_mul_f32_e32 v74, 0x3dd53b94, v75
	global_store_dwordx4 v[68:69], v[42:45], off sc1
	v_pk_mul_f32 v[56:57], v[56:57], v[74:75] op_sel_hi:[1,0]
	v_pk_mul_f32 v[54:55], v[54:55], v[74:75] op_sel_hi:[1,0]
	v_cvt_pk_bf16_f32 v42, v50, v51
	v_cvt_pk_bf16_f32 v43, v52, v53
	v_cvt_pk_bf16_f32 v44, v72, v73
	v_cvt_pk_bf16_f32 v45, v80, v81
	global_store_dwordx4 v[68:69], v[42:45], off offset:256 sc1
	v_pk_mul_f32 v[48:49], v[48:49], v[74:75] op_sel_hi:[1,0]
	v_pk_mul_f32 v[38:39], v[38:39], v[74:75] op_sel_hi:[1,0]
	v_pk_mul_f32 v[44:45], v[46:47], v[74:75] op_sel_hi:[1,0]
	v_cvt_pk_bf16_f32 v42, v54, v55
	v_cvt_pk_bf16_f32 v43, v56, v57
	v_pk_mul_f32 v[40:41], v[40:41], v[74:75] op_sel_hi:[1,0]
	v_cvt_pk_bf16_f32 v44, v44, v45
	v_cvt_pk_bf16_f32 v45, v48, v49
	global_store_dwordx4 v[70:71], v[42:45], off sc1
	v_pk_mul_f32 v[34:35], v[34:35], v[76:77] op_sel_hi:[1,0]
	v_pk_mul_f32 v[22:23], v[22:23], v[76:77] op_sel_hi:[1,0]
	v_pk_mul_f32 v[42:43], v[32:33], v[74:75] op_sel_hi:[1,0]
	v_pk_mul_f32 v[32:33], v[30:31], v[74:75] op_sel_hi:[1,0]
	v_cvt_pk_bf16_f32 v30, v38, v39
	v_cvt_pk_bf16_f32 v31, v40, v41
	v_pk_mul_f32 v[24:25], v[24:25], v[76:77] op_sel_hi:[1,0]
	v_cvt_pk_bf16_f32 v32, v32, v33
	v_cvt_pk_bf16_f32 v33, v42, v43
	global_store_dwordx4 v[70:71], v[30:33], off offset:256 sc1
	v_mul_f32_e32 v78, 0x3dd53b94, v77
	v_pk_mul_f32 v[18:19], v[18:19], v[78:79] op_sel_hi:[1,0]
	v_or_b32_e32 v30, 32, v66
	v_mad_i64_i32 v[30:31], s[0:1], v30, s45, v[144:145]
	v_lshl_add_u64 v[30:31], v[30:31], 0, v[146:147]
	v_pk_mul_f32 v[32:33], v[36:37], v[76:77] op_sel_hi:[1,0]
	v_pk_mul_f32 v[36:37], v[28:29], v[76:77] op_sel_hi:[1,0]
	v_pk_mul_f32 v[28:29], v[26:27], v[76:77] op_sel_hi:[1,0]
	v_cvt_pk_bf16_f32 v26, v34, v35
	v_cvt_pk_bf16_f32 v27, v32, v33
	v_pk_mul_f32 v[8:9], v[8:9], v[78:79] op_sel_hi:[1,0]
	v_cvt_pk_bf16_f32 v28, v28, v29
	v_cvt_pk_bf16_f32 v29, v36, v37
	global_store_dwordx4 v[30:31], v[26:29], off sc1
	v_pk_mul_f32 v[6:7], v[6:7], v[78:79] op_sel_hi:[1,0]
	s_and_b64 vcc, exec, s[20:21]
	v_pk_mul_f32 v[26:27], v[16:17], v[76:77] op_sel_hi:[1,0]
	v_pk_mul_f32 v[16:17], v[14:15], v[76:77] op_sel_hi:[1,0]
	v_cvt_pk_bf16_f32 v14, v22, v23
	v_cvt_pk_bf16_f32 v15, v24, v25
	s_mov_b32 s20, s46
	v_cvt_pk_bf16_f32 v16, v16, v17
	v_cvt_pk_bf16_f32 v17, v26, v27
	global_store_dwordx4 v[30:31], v[14:17], off offset:256 sc1
	s_mov_b32 s21, s47
	s_mov_b64 s[6:7], s[24:25]
	v_or_b32_e32 v14, 48, v66
	v_mad_i64_i32 v[14:15], s[0:1], v14, s45, v[144:145]
	v_lshl_add_u64 v[14:15], v[14:15], 0, v[146:147]
	v_pk_mul_f32 v[16:17], v[20:21], v[78:79] op_sel_hi:[1,0]
	v_pk_mul_f32 v[20:21], v[12:13], v[78:79] op_sel_hi:[1,0]
	v_pk_mul_f32 v[12:13], v[10:11], v[78:79] op_sel_hi:[1,0]
	v_cvt_pk_bf16_f32 v10, v18, v19
	v_cvt_pk_bf16_f32 v11, v16, v17
	s_mov_b64 s[0:1], s[18:19]
	v_cvt_pk_bf16_f32 v12, v12, v13
	v_cvt_pk_bf16_f32 v13, v20, v21
	global_store_dwordx4 v[14:15], v[10:13], off sc1
	s_nop 1
	v_pk_mul_f32 v[10:11], v[4:5], v[78:79] op_sel_hi:[1,0]
	v_pk_mul_f32 v[4:5], v[2:3], v[78:79] op_sel_hi:[1,0]
	v_cvt_pk_bf16_f32 v2, v6, v7
	v_cvt_pk_bf16_f32 v3, v8, v9
	s_nop 0
	v_cvt_pk_bf16_f32 v4, v4, v5
	v_cvt_pk_bf16_f32 v5, v10, v11
	global_store_dwordx4 v[14:15], v[2:5], off offset:256 sc1
	s_cbranch_vccz .LBB0_1335
	s_branch .LBB0_1349
